# kernel entry: the three sequential kernarg s_load_dwordx16 batches issued together at entry (one scalar round trip instead of three)
# baseline (speedup 1.0000x reference)
_Z14fwd_megakernel6Params:
	s_mov_b32 s22, s2
	s_load_dwordx8 s[24:31], s[0:1], 0xe0
	s_load_dwordx8 s[4:11], s[0:1], 0xc0
	s_load_dword s2, s[0:1], 0x108
	s_load_dwordx2 s[34:35], s[0:1], 0x100
	s_load_dwordx16 s[36:51], s[0:1], 0x0
	s_load_dwordx16 s[52:67], s[0:1], 0x40
	s_load_dwordx16 s[68:83], s[0:1], 0x80
	v_and_b32_e32 v128, 0x3ff, v0
	v_cmp_gt_u32_e32 vcc, 2, v128
	s_waitcnt lgkmcnt(0)
	v_writelane_b32 v255, s2, 0
	s_add_u32 s2, s0, 0x100
	s_addc_u32 s3, s1, 0
	s_and_saveexec_b64 s[12:13], vcc
	v_lshl_add_u32 v1, v128, 2, 0
	v_add_u32_e32 v1, 0x23fc0, v1
	v_mov_b32_e32 v2, 0
	ds_write_b32 v1, v2
	s_or_b64 exec, exec, s[12:13]
	s_waitcnt lgkmcnt(0)
	s_barrier
	s_add_u32 s96, s28, 0x2fe0000
	s_getreg_b32 s12, hwreg(HW_REG_XCC_ID, 0, 4)
	s_addc_u32 s97, s29, 0
	s_and_b32 s93, s12, 15
	v_cmp_eq_u32_e64 s[94:95], 0, v128
	s_and_saveexec_b64 s[12:13], s[94:95]
	s_cbranch_execz .LBB0_5
	s_mov_b64 s[14:15], exec
	v_mbcnt_lo_u32_b32 v1, s14, 0
	v_mbcnt_hi_u32_b32 v1, s15, v1
	v_cmp_eq_u32_e32 vcc, 0, v1
	s_and_b64 s[16:17], exec, vcc
	s_mov_b64 exec, s[16:17]
	s_cbranch_execz .LBB0_5
	s_lshl_b32 s16, s93, 8
	s_bcnt1_i32_b64 s14, s[14:15]
	v_mov_b32_e32 v1, s16
	v_mov_b32_e32 v2, s14
	global_atomic_add v1, v2, s[96:97] offset:1024
.LBB0_5:
	s_or_b64 exec, exec, s[12:13]
	s_cmp_gt_i32 s30, -1
	s_waitcnt lgkmcnt(0)
	v_writelane_b32 v255, s36, 1
	s_nop 1
	v_writelane_b32 v255, s37, 2
	v_writelane_b32 v255, s38, 3
	v_writelane_b32 v255, s39, 4
	v_writelane_b32 v255, s40, 5
	v_writelane_b32 v255, s41, 6
	v_writelane_b32 v255, s42, 7
	v_writelane_b32 v255, s43, 8
	v_writelane_b32 v255, s44, 9
	v_writelane_b32 v255, s45, 10
	v_writelane_b32 v255, s46, 11
	v_writelane_b32 v255, s47, 12
	v_writelane_b32 v255, s48, 13
	v_writelane_b32 v255, s49, 14
	v_writelane_b32 v255, s50, 15
	v_writelane_b32 v255, s51, 16
	s_cbranch_scc1 .LBB0_17
	v_lshrrev_b32_e32 v1, 20, v0
	v_lshrrev_b32_e32 v0, 10, v0
	v_or_b32_e32 v0, v0, v1
	s_movk_i32 s12, 0x3ff
	v_and_or_b32 v0, v0, s12, v128
	v_cmp_eq_u32_e32 vcc, 0, v0
	s_barrier
	s_and_saveexec_b64 s[12:13], vcc
	s_cbranch_execz .LBB0_16
	buffer_wbl2 sc1
	s_waitcnt vmcnt(0)
	s_load_dwordx2 s[14:15], s[2:3], 0x58
	v_mov_b32_e32 v2, 0
	s_mov_b64 s[16:17], exec
	v_mbcnt_lo_u32_b32 v1, s16, 0
	v_mbcnt_hi_u32_b32 v1, s17, v1
	s_waitcnt lgkmcnt(0)
	global_load_dword v0, v2, s[14:15] offset:40
	v_cmp_eq_u32_e32 vcc, 0, v1
	s_and_saveexec_b64 s[18:19], vcc
	s_cbranch_execz .LBB0_9
	s_bcnt1_i32_b64 s16, s[16:17]
	v_mov_b32_e32 v3, s16
	global_atomic_add v3, v2, v3, s[14:15] offset:32 sc0

.LBB0_17:
	s_add_u32 s12, s28, 0x2f00000
	s_addc_u32 s13, s29, 0
	s_cmp_lt_i32 s30, 1
	s_cselect_b64 s[0:1], -1, 0
	s_waitcnt lgkmcnt(0)
	s_mov_b64 s[36:37], s[68:69]
	s_mov_b64 s[38:39], s[70:71]
	s_mov_b64 s[40:41], s[72:73]
	s_mov_b64 s[42:43], s[74:75]
	s_mov_b64 s[44:45], s[76:77]
	s_mov_b64 s[46:47], s[78:79]
	s_mov_b64 s[48:49], s[80:81]
	s_mov_b64 s[50:51], s[82:83]
	v_writelane_b32 v255, s36, 17
	s_cmp_gt_i32 s31, 0
	s_cselect_b64 s[14:15], -1, 0
	v_writelane_b32 v255, s37, 18
	v_writelane_b32 v255, s38, 19
	v_writelane_b32 v255, s39, 20
	v_writelane_b32 v255, s40, 21
	v_writelane_b32 v255, s41, 22
	v_writelane_b32 v255, s42, 23
	v_writelane_b32 v255, s43, 24
	v_writelane_b32 v255, s44, 25
	v_writelane_b32 v255, s45, 26
	v_writelane_b32 v255, s46, 27
	v_writelane_b32 v255, s47, 28
	v_writelane_b32 v255, s48, 29
	v_writelane_b32 v255, s49, 30
	v_writelane_b32 v255, s50, 31
	s_and_b64 s[82:83], s[0:1], s[14:15]
	v_writelane_b32 v255, s51, 32
	s_andn2_b64 vcc, exec, s[82:83]
	s_mov_b32 s18, 0
	s_cbranch_vccnz .LBB0_227
	v_lshrrev_b32_e32 v8, 9, v128
	v_sub_u32_e32 v10, 14, v8
	v_and_b32_e32 v2, 14, v10
	v_lshlrev_b32_e32 v1, 2, v128
	v_and_b32_e32 v0, 7, v128
	v_add_u32_e32 v129, 0x200, v128
	v_add_u32_e32 v4, 0, v1
	v_add_u32_e32 v2, 2, v2
	v_mov_b32_e32 v3, 0
	v_add_u32_e32 v11, 0x12800, v4
	v_and_b32_e32 v9, 28, v2
	s_mov_b64 s[16:17], 0
	s_movk_i32 s19, 0x4020
	v_mov_b64_e32 v[6:7], s[56:57]
	v_lshlrev_b32_e32 v2, 2, v0
	s_movk_i32 s20, 0x2000
	v_mov_b64_e32 v[4:5], v[128:129]
